# attention: the 512 sample queries are assigned XCD-aligned (each XCD handles two sample streams, whose cached K/V then stays in that XCD's L2) instead of every XCD touching all 16 streams
# speedup vs baseline: 1.0042x; 1.0019x over previous
; __device__ __forceinline__ void phase_attn(KP kp, int l, unsigned char* shm) {
;     ...
;       float mx = -1e30f;
; #pragma unroll
;       for (int kb = 0; kb < 16; ++kb)
; #pragma unroll
;         for (int j = 0; j < 4; ++j) {
;           const int key = kb * 16 + kg * 4 + j;
;           lg[kb][j] = key < cnt ? lg[kb][j] : -1e30f;
;           mx = fmaxf(mx, lg[kb][j]);
;         }
;       mx = fmaxf(mx, __shfl_xor(mx, 16));
;       mx = fmaxf(mx, __shfl_xor(mx, 32));
;       float sum = 0.f;
; #pragma unroll
;       for (int kb = 0; kb < 16; ++kb)
; #pragma unroll
;         for (int j = 0; j < 4; ++j) { lg[kb][j] = __builtin_amdgcn_exp2f(lg[kb][j] - mx); sum += lg[kb][j]; }
;       sum += __shfl_xor(sum, 16);
;       sum += __shfl_xor(sum, 32);
;       const float inv = 1.f / sum;
.Lattn_nomask_4:
	v_max3_f32 v176, v32, v33, v34
	v_max3_f32 v176, v176, v35, v36
	v_max3_f32 v176, v176, v37, v38
	v_max3_f32 v176, v176, v39, v40
	v_max3_f32 v176, v176, v41, v42
	v_max3_f32 v176, v176, v43, v44
	v_max3_f32 v176, v176, v45, v46
	v_max3_f32 v176, v176, v47, v48
	v_max3_f32 v176, v176, v49, v50
	v_max3_f32 v176, v176, v51, v52
	v_max3_f32 v176, v176, v53, v54
	v_max3_f32 v176, v176, v55, v56
	v_max3_f32 v176, v176, v57, v58
	v_max3_f32 v176, v176, v59, v60
	v_max3_f32 v176, v176, v61, v62
	v_max3_f32 v176, v176, v63, v64
	v_max3_f32 v176, v176, v65, v66
	v_max3_f32 v176, v176, v67, v68
	v_max3_f32 v176, v176, v69, v70
	v_max3_f32 v176, v176, v71, v72
	v_max3_f32 v176, v176, v73, v74
	v_max3_f32 v176, v176, v75, v76
	v_max3_f32 v176, v176, v77, v78
	v_max3_f32 v176, v176, v79, v80
	v_max3_f32 v176, v176, v81, v82
	v_max3_f32 v176, v176, v83, v84
	v_max3_f32 v176, v176, v85, v86
	v_max3_f32 v176, v176, v87, v88
	v_max3_f32 v176, v176, v89, v90
	v_max3_f32 v176, v176, v91, v92
	v_max3_f32 v176, v176, v93, v94
	v_max_f32_e32 v176, v176, v95
	ds_bpermute_b32 v197, v191, v176
	s_waitcnt lgkmcnt(0)
	v_max_f32_e32 v176, v176, v197
	ds_bpermute_b32 v197, v192, v176
	s_waitcnt lgkmcnt(0)
	v_max_f32_e32 v176, v176, v197
	v_mov_b32_e32 v177, v176
	v_pk_add_f32 v[32:33], v[32:33], v[176:177] neg_lo:[0,1] neg_hi:[0,1]
	v_pk_add_f32 v[34:35], v[34:35], v[176:177] neg_lo:[0,1] neg_hi:[0,1]
	v_pk_add_f32 v[36:37], v[36:37], v[176:177] neg_lo:[0,1] neg_hi:[0,1]
	v_pk_add_f32 v[38:39], v[38:39], v[176:177] neg_lo:[0,1] neg_hi:[0,1]
	v_pk_add_f32 v[40:41], v[40:41], v[176:177] neg_lo:[0,1] neg_hi:[0,1]
	v_pk_add_f32 v[42:43], v[42:43], v[176:177] neg_lo:[0,1] neg_hi:[0,1]
	v_pk_add_f32 v[44:45], v[44:45], v[176:177] neg_lo:[0,1] neg_hi:[0,1]
	v_pk_add_f32 v[46:47], v[46:47], v[176:177] neg_lo:[0,1] neg_hi:[0,1]
	v_pk_add_f32 v[48:49], v[48:49], v[176:177] neg_lo:[0,1] neg_hi:[0,1]
	v_pk_add_f32 v[50:51], v[50:51], v[176:177] neg_lo:[0,1] neg_hi:[0,1]
	v_pk_add_f32 v[52:53], v[52:53], v[176:177] neg_lo:[0,1] neg_hi:[0,1]
	v_pk_add_f32 v[54:55], v[54:55], v[176:177] neg_lo:[0,1] neg_hi:[0,1]
	v_pk_add_f32 v[56:57], v[56:57], v[176:177] neg_lo:[0,1] neg_hi:[0,1]
	v_pk_add_f32 v[58:59], v[58:59], v[176:177] neg_lo:[0,1] neg_hi:[0,1]
	v_pk_add_f32 v[60:61], v[60:61], v[176:177] neg_lo:[0,1] neg_hi:[0,1]
	v_pk_add_f32 v[62:63], v[62:63], v[176:177] neg_lo:[0,1] neg_hi:[0,1]
	v_pk_add_f32 v[64:65], v[64:65], v[176:177] neg_lo:[0,1] neg_hi:[0,1]
	v_pk_add_f32 v[66:67], v[66:67], v[176:177] neg_lo:[0,1] neg_hi:[0,1]
	v_pk_add_f32 v[68:69], v[68:69], v[176:177] neg_lo:[0,1] neg_hi:[0,1]
	v_pk_add_f32 v[70:71], v[70:71], v[176:177] neg_lo:[0,1] neg_hi:[0,1]
	v_pk_add_f32 v[72:73], v[72:73], v[176:177] neg_lo:[0,1] neg_hi:[0,1]
	v_pk_add_f32 v[74:75], v[74:75], v[176:177] neg_lo:[0,1] neg_hi:[0,1]
	v_pk_add_f32 v[76:77], v[76:77], v[176:177] neg_lo:[0,1] neg_hi:[0,1]
	v_pk_add_f32 v[78:79], v[78:79], v[176:177] neg_lo:[0,1] neg_hi:[0,1]
	v_pk_add_f32 v[80:81], v[80:81], v[176:177] neg_lo:[0,1] neg_hi:[0,1]
	v_pk_add_f32 v[82:83], v[82:83], v[176:177] neg_lo:[0,1] neg_hi:[0,1]
	v_pk_add_f32 v[84:85], v[84:85], v[176:177] neg_lo:[0,1] neg_hi:[0,1]
	v_pk_add_f32 v[86:87], v[86:87], v[176:177] neg_lo:[0,1] neg_hi:[0,1]
	v_pk_add_f32 v[88:89], v[88:89], v[176:177] neg_lo:[0,1] neg_hi:[0,1]
	v_pk_add_f32 v[90:91], v[90:91], v[176:177] neg_lo:[0,1] neg_hi:[0,1]
	v_pk_add_f32 v[92:93], v[92:93], v[176:177] neg_lo:[0,1] neg_hi:[0,1]
	v_pk_add_f32 v[94:95], v[94:95], v[176:177] neg_lo:[0,1] neg_hi:[0,1]
	v_exp_f32_e32 v32, v32
	v_exp_f32_e32 v33, v33
	v_exp_f32_e32 v34, v34
	v_exp_f32_e32 v35, v35
	v_exp_f32_e32 v36, v36
	v_exp_f32_e32 v37, v37
	v_pk_add_f32 v[178:179], v[32:33], v[34:35]
	v_exp_f32_e32 v38, v38
	v_exp_f32_e32 v39, v39
	v_pk_add_f32 v[178:179], v[178:179], v[36:37]
	v_exp_f32_e32 v40, v40
	v_exp_f32_e32 v41, v41
	v_pk_add_f32 v[178:179], v[178:179], v[38:39]
	v_exp_f32_e32 v42, v42
	v_exp_f32_e32 v43, v43
	v_pk_add_f32 v[178:179], v[178:179], v[40:41]
	v_exp_f32_e32 v44, v44
	v_exp_f32_e32 v45, v45
	v_pk_add_f32 v[178:179], v[178:179], v[42:43]
	v_exp_f32_e32 v46, v46
	v_exp_f32_e32 v47, v47
	v_pk_add_f32 v[178:179], v[178:179], v[44:45]
	v_exp_f32_e32 v48, v48
	v_exp_f32_e32 v49, v49
	v_pk_add_f32 v[178:179], v[178:179], v[46:47]
	v_exp_f32_e32 v50, v50
	v_exp_f32_e32 v51, v51
	v_pk_add_f32 v[178:179], v[178:179], v[48:49]
	v_exp_f32_e32 v52, v52
	v_exp_f32_e32 v53, v53
	v_pk_add_f32 v[178:179], v[178:179], v[50:51]
	v_exp_f32_e32 v54, v54
	v_exp_f32_e32 v55, v55
	v_pk_add_f32 v[178:179], v[178:179], v[52:53]
	v_exp_f32_e32 v56, v56
	v_exp_f32_e32 v57, v57
	v_pk_add_f32 v[178:179], v[178:179], v[54:55]
	v_exp_f32_e32 v58, v58
	v_exp_f32_e32 v59, v59
	v_pk_add_f32 v[178:179], v[178:179], v[56:57]
	v_exp_f32_e32 v60, v60
	v_exp_f32_e32 v61, v61
	v_pk_add_f32 v[178:179], v[178:179], v[58:59]
	v_exp_f32_e32 v62, v62
	v_exp_f32_e32 v63, v63
	v_pk_add_f32 v[178:179], v[178:179], v[60:61]
	v_exp_f32_e32 v64, v64
	v_exp_f32_e32 v65, v65
	v_pk_add_f32 v[178:179], v[178:179], v[62:63]
	v_exp_f32_e32 v66, v66
	v_exp_f32_e32 v67, v67
	v_pk_add_f32 v[178:179], v[178:179], v[64:65]
	v_exp_f32_e32 v68, v68
	v_exp_f32_e32 v69, v69
	v_pk_add_f32 v[178:179], v[178:179], v[66:67]
	v_exp_f32_e32 v70, v70
	v_exp_f32_e32 v71, v71
	v_pk_add_f32 v[178:179], v[178:179], v[68:69]
	v_exp_f32_e32 v72, v72
	v_exp_f32_e32 v73, v73
	v_pk_add_f32 v[178:179], v[178:179], v[70:71]
	v_exp_f32_e32 v74, v74
	v_exp_f32_e32 v75, v75
	v_pk_add_f32 v[178:179], v[178:179], v[72:73]
	v_exp_f32_e32 v76, v76
	v_exp_f32_e32 v77, v77
	v_pk_add_f32 v[178:179], v[178:179], v[74:75]
; __device__ __forceinline__ void phase_attn(KP kp, int l, unsigned char* shm) {
;     ...
;       float sum = 0.f;
; #pragma unroll
;       for (int kb = 0; kb < 16; ++kb)
; #pragma unroll
;         for (int j = 0; j < 4; ++j) { lg[kb][j] = __builtin_amdgcn_exp2f(lg[kb][j] - mx); sum += lg[kb][j]; }
;       sum += __shfl_xor(sum, 16);
;       sum += __shfl_xor(sum, 32);
;       const float inv = 1.f / sum;
;       bf16x8 pf[8];
; #pragma unroll
;       for (int s8 = 0; s8 < 8; ++s8) {
;         u32x4 pk;
;         pk[0] = cvt_pk_bf16(lg[2 * s8][0], lg[2 * s8][1]);
;         pk[1] = cvt_pk_bf16(lg[2 * s8][2], lg[2 * s8][3]);
;         pk[2] = cvt_pk_bf16(lg[2 * s8 + 1][0], lg[2 * s8 + 1][1]);
;         pk[3] = cvt_pk_bf16(lg[2 * s8 + 1][2], lg[2 * s8 + 1][3]);
;         pf[s8] = __builtin_bit_cast(bf16x8, pk);
;       }
;       f32x4 oacc[4];
; #pragma unroll
;       for (int c = 0; c < 4; ++c) oacc[c] = (f32x4){0.f, 0.f, 0.f, 0.f};
;       for (int repV = 0; repV < ((PROBE & 256) ? 2 : 1); ++repV)
;       {
;         if (repV) {
; #pragma unroll
;           for (int c = 0; c < 4; ++c) oacc[c] = (f32x4){0.f, 0.f, 0.f, 0.f};
;         }
; #pragma unroll
;         for (int i = 16; i < 32; ++i) {
;           const int idx = selw[i * 8 + ks8];
;           vr[i] = *(const u32x4*)(vbase + (size_t)idx * 128 + kvh * 64 + dc * 8);
;         }
; #pragma unroll
;         for (int s8 = 0; s8 < 8; ++s8) {
; #pragma unroll
;           for (int it = 0; it < 4; ++it) *(u32x4*)(tileb + (it * 8 + ks8) * 144 + dc * 16) = vr[s8 * 4 + it];
;           u32x2 t0, t1, t2, t3, t4, t5, t6, t7;
;           asm volatile(
;               "ds_read_b64_tr_b16 %0, %8\n\tds_read_b64_tr_b16 %1, %8 offset:2304\n\t"
;               "ds_read_b64_tr_b16 %2, %8 offset:32\n\tds_read_b64_tr_b16 %3, %8 offset:2336\n\t"
;               "ds_read_b64_tr_b16 %4, %8 offset:64\n\tds_read_b64_tr_b16 %5, %8 offset:2368\n\t"
;               "ds_read_b64_tr_b16 %6, %8 offset:96\n\tds_read_b64_tr_b16 %7, %8 offset:2400\n\t"
;               "s_waitcnt lgkmcnt(0)"
;               : "=&v"(t0), "=&v"(t1), "=&v"(t2), "=&v"(t3), "=&v"(t4), "=&v"(t5), "=&v"(t6), "=&v"(t7)
;               : "v"(tr_addr)
;               : "memory");
;           const bf16x8 a0 = __builtin_bit_cast(bf16x8, (u32x4){t0[0], t0[1], t1[0], t1[1]});
;           const bf16x8 a1 = __builtin_bit_cast(bf16x8, (u32x4){t2[0], t2[1], t3[0], t3[1]});
	v_exp_f32_e32 v78, v78
	v_exp_f32_e32 v79, v79
	v_pk_add_f32 v[178:179], v[178:179], v[76:77]
	v_exp_f32_e32 v80, v80
	v_exp_f32_e32 v81, v81
	v_pk_add_f32 v[178:179], v[178:179], v[78:79]
	v_exp_f32_e32 v82, v82
	v_exp_f32_e32 v83, v83
	v_pk_add_f32 v[178:179], v[178:179], v[80:81]
	v_exp_f32_e32 v84, v84
	v_exp_f32_e32 v85, v85
	v_pk_add_f32 v[178:179], v[178:179], v[82:83]
	v_exp_f32_e32 v86, v86
	v_exp_f32_e32 v87, v87
	v_pk_add_f32 v[178:179], v[178:179], v[84:85]
	v_exp_f32_e32 v88, v88
	v_exp_f32_e32 v89, v89
	v_pk_add_f32 v[178:179], v[178:179], v[86:87]
	v_exp_f32_e32 v90, v90
	v_exp_f32_e32 v91, v91
	v_pk_add_f32 v[178:179], v[178:179], v[88:89]
	v_exp_f32_e32 v92, v92
	v_exp_f32_e32 v93, v93
	v_pk_add_f32 v[178:179], v[178:179], v[90:91]
	v_exp_f32_e32 v94, v94
	v_exp_f32_e32 v95, v95
	v_pk_add_f32 v[178:179], v[178:179], v[92:93]
	s_nop 0
	v_pk_add_f32 v[178:179], v[178:179], v[94:95]
	v_add_f32_e32 v210, v178, v179
	ds_bpermute_b32 v197, v191, v210
	v_cvt_pk_bf16_f32 v96, v32, v33
	v_cvt_pk_bf16_f32 v97, v34, v35
	v_cvt_pk_bf16_f32 v98, v36, v37
	v_cvt_pk_bf16_f32 v99, v38, v39
	v_cvt_pk_bf16_f32 v100, v40, v41
	v_cvt_pk_bf16_f32 v101, v42, v43
	v_cvt_pk_bf16_f32 v102, v44, v45
	v_cvt_pk_bf16_f32 v103, v46, v47
	v_cvt_pk_bf16_f32 v104, v48, v49
	v_cvt_pk_bf16_f32 v105, v50, v51
	v_cvt_pk_bf16_f32 v106, v52, v53
	v_cvt_pk_bf16_f32 v107, v54, v55
	v_cvt_pk_bf16_f32 v108, v56, v57
	v_cvt_pk_bf16_f32 v109, v58, v59
	v_cvt_pk_bf16_f32 v110, v60, v61
	v_cvt_pk_bf16_f32 v111, v62, v63
	s_waitcnt lgkmcnt(0)
	v_add_f32_e32 v210, v210, v197
	ds_bpermute_b32 v197, v192, v210
	v_cvt_pk_bf16_f32 v112, v64, v65
	v_cvt_pk_bf16_f32 v113, v66, v67
	v_cvt_pk_bf16_f32 v114, v68, v69
	v_cvt_pk_bf16_f32 v115, v70, v71
	v_cvt_pk_bf16_f32 v116, v72, v73
	v_cvt_pk_bf16_f32 v117, v74, v75
	v_cvt_pk_bf16_f32 v118, v76, v77
	v_cvt_pk_bf16_f32 v119, v78, v79
	v_cvt_pk_bf16_f32 v120, v80, v81
	v_cvt_pk_bf16_f32 v121, v82, v83
	v_cvt_pk_bf16_f32 v122, v84, v85
	v_cvt_pk_bf16_f32 v123, v86, v87
	v_cvt_pk_bf16_f32 v124, v88, v89
	v_cvt_pk_bf16_f32 v125, v90, v91
	v_cvt_pk_bf16_f32 v126, v92, v93
	v_cvt_pk_bf16_f32 v127, v94, v95
	s_waitcnt lgkmcnt(0)
	v_add_f32_e32 v210, v210, v197
	v_rcp_f32_e32 v208, v210
	s_waitcnt vmcnt(8)
	ds_read_b64_tr_b16 v[160:161], v182 offset:0
	ds_read_b64_tr_b16 v[162:163], v182 offset:2048
	ds_read_b64_tr_b16 v[164:165], v183 offset:0
	ds_read_b64_tr_b16 v[166:167], v183 offset:2048
	ds_read_b64_tr_b16 v[168:169], v184 offset:0
	ds_read_b64_tr_b16 v[170:171], v184 offset:2048
	ds_read_b64_tr_b16 v[172:173], v185 offset:0
	ds_read_b64_tr_b16 v[174:175], v185 offset:2048
	s_mov_b32 m0, s49
	s_nop 0
	global_load_lds_dwordx4 v12, s[22:23]
	global_load_lds_dwordx4 v13, s[22:23] offset:1024
	global_load_lds_dwordx4 v14, s[22:23] offset:2048
	global_load_lds_dwordx4 v15, s[22:23] offset:3072
	s_waitcnt lgkmcnt(0)
	v_mfma_f32_16x16x32_bf16 v[128:131], v[160:163], v[96:99], 0
	v_mfma_f32_16x16x32_bf16 v[132:135], v[164:167], v[96:99], 0
	v_mfma_f32_16x16x32_bf16 v[136:139], v[168:171], v[96:99], 0
	v_mfma_f32_16x16x32_bf16 v[140:143], v[172:175], v[96:99], 0
	s_waitcnt vmcnt(8)
	ds_read_b64_tr_b16 v[160:161], v182 offset:4096
	ds_read_b64_tr_b16 v[162:163], v182 offset:6144
	ds_read_b64_tr_b16 v[164:165], v183 offset:4096
	ds_read_b64_tr_b16 v[166:167], v183 offset:6144
	ds_read_b64_tr_b16 v[168:169], v184 offset:4096
	ds_read_b64_tr_b16 v[170:171], v184 offset:6144
	ds_read_b64_tr_b16 v[172:173], v185 offset:4096
	ds_read_b64_tr_b16 v[174:175], v185 offset:6144
	s_mov_b32 m0, s46
	s_nop 0
	global_load_lds_dwordx4 v16, s[22:23]
	global_load_lds_dwordx4 v18, s[22:23] offset:1024
	global_load_lds_dwordx4 v19, s[22:23] offset:2048
	global_load_lds_dwordx4 v20, s[22:23] offset:3072
	s_waitcnt lgkmcnt(0)
	v_mfma_f32_16x16x32_bf16 v[128:131], v[160:163], v[100:103], v[128:131]
	v_mfma_f32_16x16x32_bf16 v[132:135], v[164:167], v[100:103], v[132:135]
	v_mfma_f32_16x16x32_bf16 v[136:139], v[168:171], v[100:103], v[136:139]
	v_mfma_f32_16x16x32_bf16 v[140:143], v[172:175], v[100:103], v[140:143]
	s_waitcnt vmcnt(8)
	ds_read_b64_tr_b16 v[160:161], v182 offset:8192
	ds_read_b64_tr_b16 v[162:163], v182 offset:10240
	ds_read_b64_tr_b16 v[164:165], v183 offset:8192
	ds_read_b64_tr_b16 v[166:167], v183 offset:10240
	ds_read_b64_tr_b16 v[168:169], v184 offset:8192
	ds_read_b64_tr_b16 v[170:171], v184 offset:10240
	ds_read_b64_tr_b16 v[172:173], v185 offset:8192
	ds_read_b64_tr_b16 v[174:175], v185 offset:10240
	s_mov_b32 m0, s47
	s_nop 0
	global_load_lds_dwordx4 v21, s[22:23]
	global_load_lds_dwordx4 v22, s[22:23] offset:1024
	global_load_lds_dwordx4 v23, s[22:23] offset:2048
	global_load_lds_dwordx4 v24, s[22:23] offset:3072
	s_waitcnt lgkmcnt(0)
	v_mfma_f32_16x16x32_bf16 v[128:131], v[160:163], v[104:107], v[128:131]
	v_mfma_f32_16x16x32_bf16 v[132:135], v[164:167], v[104:107], v[132:135]
	v_mfma_f32_16x16x32_bf16 v[136:139], v[168:171], v[104:107], v[136:139]
	v_mfma_f32_16x16x32_bf16 v[140:143], v[172:175], v[104:107], v[140:143]
	s_waitcnt vmcnt(8)
	ds_read_b64_tr_b16 v[160:161], v182 offset:12288
	ds_read_b64_tr_b16 v[162:163], v182 offset:14336
	ds_read_b64_tr_b16 v[164:165], v183 offset:12288
	ds_read_b64_tr_b16 v[166:167], v183 offset:14336
	ds_read_b64_tr_b16 v[168:169], v184 offset:12288
	ds_read_b64_tr_b16 v[170:171], v184 offset:14336
	ds_read_b64_tr_b16 v[172:173], v185 offset:12288
	ds_read_b64_tr_b16 v[174:175], v185 offset:14336
	s_mov_b32 m0, s48
	s_nop 0
	global_load_lds_dwordx4 v25, s[22:23]
	global_load_lds_dwordx4 v26, s[22:23] offset:1024
	global_load_lds_dwordx4 v27, s[22:23] offset:2048
	global_load_lds_dwordx4 v28, s[22:23] offset:3072
	s_waitcnt lgkmcnt(0)
; __device__ __forceinline__ void phase_attn(KP kp, int l, unsigned char* shm) {
;     ...
;   for (int q = blockIdx.x * 8 + w; q < MT; q += gridDim.x * 8) {
;     int r = q;
;     if (gridDim.x == 256 && q < MP) r = ((q >> 3) & 7) * 4096 + (q >> 11) * 256 + ((q >> 6) & 31) * 8 + (q & 7);
;     const bf16_t *kbase, *vbase;
;     int n;
;     if (r < MP) {
;       const int b = r >> 12, t = r & 4095;
;       kbase = (const bf16_t*)(ws + W_KP) + (size_t)b * 4096 * 128;
;       vbase = (const bf16_t*)(ws + W_VP) + (size_t)b * 4096 * 128;
;       n = ((t >> 6) + 1) * 64;
;     } else {
;       const int sb = (r - MP) >> 5;
;       kbase = (const bf16_t*)(ws + W_KS) + (size_t)(l * 16 + sb) * 2080 * 128;
;       vbase = (const bf16_t*)(ws + W_VS) + (size_t)(l * 16 + sb) * 2080 * 128;
;       n = 2080;
;     }
;     ...
;           oacc[0] = __builtin_amdgcn_mfma_f32_16x16x32_bf16(a0, pf[s8], oacc[0], 0, 0, 0);
;           oacc[1] = __builtin_amdgcn_mfma_f32_16x16x32_bf16(a1, pf[s8], oacc[1], 0, 0, 0);
;           oacc[2] = __builtin_amdgcn_mfma_f32_16x16x32_bf16(a2, pf[s8], oacc[2], 0, 0, 0);
;           oacc[3] = __builtin_amdgcn_mfma_f32_16x16x32_bf16(a3, pf[s8], oacc[3], 0, 0, 0);
;           if (kvh == 0 && s8 == 3) {
; #pragma unroll
;             for (int k8 = 0; k8 < 8; ++k8) {
;               const int idx = selw[k8 * 16 + nn];
;               const bf16_t* kp = kbase + (size_t)idx * 128 + 64 + kg * 8;
;               kpre[k8][0] = *(const bf16x8*)kp;
;               kpre[k8][1] = *(const bf16x8*)(kp + 32);
;             }
;           }
;         }
;         __builtin_amdgcn_sched_barrier(0);
;       }
;       if (nn < 4) {
; #pragma unroll
;         for (int c = 0; c < 4; ++c) {
;           u32x2 ow;
;           ow[0] = cvt_pk_bf16(oacc[c][0] * inv, oacc[c][1] * inv);
;           ow[1] = cvt_pk_bf16(oacc[c][2] * inv, oacc[c][3] * inv);
;           *(u32x2*)((bf16_t*)(ws + W_OA) + (size_t)r * 512 + (kvh * 4 + nn) * 64 + 16 * c + 4 * kg) = ow;
;         }
	v_mfma_f32_16x16x32_bf16 v[128:131], v[160:163], v[108:111], v[128:131]
	v_mfma_f32_16x16x32_bf16 v[132:135], v[164:167], v[108:111], v[132:135]
	v_mfma_f32_16x16x32_bf16 v[136:139], v[168:171], v[108:111], v[136:139]
	v_mfma_f32_16x16x32_bf16 v[140:143], v[172:175], v[108:111], v[140:143]
	s_waitcnt vmcnt(8)
	ds_read_b64_tr_b16 v[160:161], v182 offset:0
	ds_read_b64_tr_b16 v[162:163], v182 offset:2048
	ds_read_b64_tr_b16 v[164:165], v183 offset:0
	ds_read_b64_tr_b16 v[166:167], v183 offset:2048
	ds_read_b64_tr_b16 v[168:169], v184 offset:0
	ds_read_b64_tr_b16 v[170:171], v184 offset:2048
	ds_read_b64_tr_b16 v[172:173], v185 offset:0
	ds_read_b64_tr_b16 v[174:175], v185 offset:2048
	s_mov_b32 m0, s49
	s_nop 0
	global_load_lds_dwordx4 v29, s[22:23]
	global_load_lds_dwordx4 v30, s[22:23] offset:1024
	global_load_lds_dwordx4 v31, s[22:23] offset:2048
	global_load_lds_dwordx4 v219, s[22:23] offset:3072
	s_waitcnt lgkmcnt(0)
	v_mfma_f32_16x16x32_bf16 v[128:131], v[160:163], v[112:115], v[128:131]
	v_mfma_f32_16x16x32_bf16 v[132:135], v[164:167], v[112:115], v[132:135]
	v_mfma_f32_16x16x32_bf16 v[136:139], v[168:171], v[112:115], v[136:139]
	v_mfma_f32_16x16x32_bf16 v[140:143], v[172:175], v[112:115], v[140:143]
	s_waitcnt vmcnt(8)
	ds_read_b64_tr_b16 v[160:161], v182 offset:4096
	ds_read_b64_tr_b16 v[162:163], v182 offset:6144
	ds_read_b64_tr_b16 v[164:165], v183 offset:4096
	ds_read_b64_tr_b16 v[166:167], v183 offset:6144
	ds_read_b64_tr_b16 v[168:169], v184 offset:4096
	ds_read_b64_tr_b16 v[170:171], v184 offset:6144
	ds_read_b64_tr_b16 v[172:173], v185 offset:4096
	ds_read_b64_tr_b16 v[174:175], v185 offset:6144
	s_mov_b32 m0, s46
	s_nop 0
	global_load_lds_dwordx4 v0, s[24:25]
	global_load_lds_dwordx4 v1, s[24:25] offset:1024
	global_load_lds_dwordx4 v2, s[24:25] offset:2048
	global_load_lds_dwordx4 v3, s[24:25] offset:3072
	s_waitcnt lgkmcnt(0)
	v_mfma_f32_16x16x32_bf16 v[128:131], v[160:163], v[116:119], v[128:131]
	v_mfma_f32_16x16x32_bf16 v[132:135], v[164:167], v[116:119], v[132:135]
	v_mfma_f32_16x16x32_bf16 v[136:139], v[168:171], v[116:119], v[136:139]
	v_mfma_f32_16x16x32_bf16 v[140:143], v[172:175], v[116:119], v[140:143]
	s_waitcnt vmcnt(8)
	ds_read_b64_tr_b16 v[160:161], v182 offset:8192
	ds_read_b64_tr_b16 v[162:163], v182 offset:10240
	ds_read_b64_tr_b16 v[164:165], v183 offset:8192
	ds_read_b64_tr_b16 v[166:167], v183 offset:10240
	ds_read_b64_tr_b16 v[168:169], v184 offset:8192
	ds_read_b64_tr_b16 v[170:171], v184 offset:10240
	ds_read_b64_tr_b16 v[172:173], v185 offset:8192
	ds_read_b64_tr_b16 v[174:175], v185 offset:10240
	s_mov_b32 m0, s47
	s_nop 0
	global_load_lds_dwordx4 v4, s[24:25]
	global_load_lds_dwordx4 v5, s[24:25] offset:1024
	global_load_lds_dwordx4 v6, s[24:25] offset:2048
	global_load_lds_dwordx4 v7, s[24:25] offset:3072
	s_waitcnt lgkmcnt(0)
	v_mfma_f32_16x16x32_bf16 v[128:131], v[160:163], v[120:123], v[128:131]
	v_mfma_f32_16x16x32_bf16 v[132:135], v[164:167], v[120:123], v[132:135]
	v_mfma_f32_16x16x32_bf16 v[136:139], v[168:171], v[120:123], v[136:139]
	v_mfma_f32_16x16x32_bf16 v[140:143], v[172:175], v[120:123], v[140:143]
	s_waitcnt vmcnt(8)
	ds_read_b64_tr_b16 v[160:161], v182 offset:12288
	ds_read_b64_tr_b16 v[162:163], v182 offset:14336
	ds_read_b64_tr_b16 v[164:165], v183 offset:12288
	ds_read_b64_tr_b16 v[166:167], v183 offset:14336
	ds_read_b64_tr_b16 v[168:169], v184 offset:12288
	ds_read_b64_tr_b16 v[170:171], v184 offset:14336
	ds_read_b64_tr_b16 v[172:173], v185 offset:12288
	ds_read_b64_tr_b16 v[174:175], v185 offset:14336
	s_mov_b32 m0, s48
	s_nop 0
	global_load_lds_dwordx4 v8, s[24:25]
	global_load_lds_dwordx4 v9, s[24:25] offset:1024
	global_load_lds_dwordx4 v10, s[24:25] offset:2048
	global_load_lds_dwordx4 v11, s[24:25] offset:3072
	s_waitcnt lgkmcnt(0)
	v_mfma_f32_16x16x32_bf16 v[128:131], v[160:163], v[124:127], v[128:131]
	v_mfma_f32_16x16x32_bf16 v[132:135], v[164:167], v[124:127], v[132:135]
	v_mfma_f32_16x16x32_bf16 v[136:139], v[168:171], v[124:127], v[136:139]
	v_mfma_f32_16x16x32_bf16 v[140:143], v[172:175], v[124:127], v[140:143]
	s_nop 7
	s_nop 3
	v_mul_f32_e32 v128, v208, v128
	v_mul_f32_e32 v129, v208, v129
	v_mul_f32_e32 v130, v208, v130
	v_mul_f32_e32 v131, v208, v131
	v_cvt_pk_bf16_f32 v200, v128, v129
	v_cvt_pk_bf16_f32 v201, v130, v131
	v_mul_f32_e32 v132, v208, v132
	v_mul_f32_e32 v133, v208, v133
	v_mul_f32_e32 v134, v208, v134
	v_mul_f32_e32 v135, v208, v135
	v_cvt_pk_bf16_f32 v202, v132, v133
	v_cvt_pk_bf16_f32 v203, v134, v135
	v_mul_f32_e32 v136, v208, v136
	v_mul_f32_e32 v137, v208, v137
	v_mul_f32_e32 v138, v208, v138
	v_mul_f32_e32 v139, v208, v139
	v_cvt_pk_bf16_f32 v204, v136, v137
	v_cvt_pk_bf16_f32 v205, v138, v139
	v_mul_f32_e32 v140, v208, v140
	v_mul_f32_e32 v141, v208, v141
	v_mul_f32_e32 v142, v208, v142
	v_mul_f32_e32 v143, v208, v143
	v_cvt_pk_bf16_f32 v206, v140, v141
	v_cvt_pk_bf16_f32 v207, v142, v143
	s_mov_b64 exec, s[42:43]
	global_store_dwordx2 v190, v[200:201], s[34:35] offset:0 nt
	global_store_dwordx2 v190, v[202:203], s[34:35] offset:32 nt
	global_store_dwordx2 v190, v[204:205], s[34:35] offset:64 nt
	global_store_dwordx2 v190, v[206:207], s[34:35] offset:96 nt
	s_mov_b64 exec, -1
	s_waitcnt vmcnt(12)
	ds_read_b128 v[160:163], v180 offset:0
	ds_read_b128 v[164:167], v181 offset:0
	ds_read_b128 v[168:171], v180 offset:2048
	ds_read_b128 v[172:175], v181 offset:2048
	s_add_i32 s50, s2, s4
	s_cmp_lg_u32 s5, 0
	s_cbranch_scc1 .Lattn_nq_7
	s_cmp_lt_i32 s50, 0x8000
	s_cbranch_scc1 .Lattn_nq_7
	s_and_b32 s6, s57, 7
	s_lshl_b32 s6, s6, 1
	s_lshr_b32 s7, s57, 7
	s_add_i32 s6, s6, s7
	s_lshl_b32 s6, s6, 5
	s_lshr_b32 s7, s57, 3
	s_and_b32 s7, s7, 15
	s_lshl_b32 s7, s7, 1
	s_add_i32 s6, s6, s7
	s_add_i32 s6, s6, s56
	s_add_i32 s6, s6, 0x8000
	s_cmp_lt_u32 s56, 2
	s_cselect_b32 s6, s6, 0x10000
	s_cmp_ge_i32 s2, 0x8000
	s_cselect_b32 s50, 0x10000, s6
